# P2: conv U-tile lines touched near the end of each attention unit (L2 warm-up)
# speedup vs baseline: 1.0022x; 1.0016x over previous
; #define SBAR() __builtin_amdgcn_sched_barrier(0)
; #define PK(k) __builtin_shufflevector(lo[k], hi[k], 0, 1, 2, 3, 4, 5, 6, 7)
; #define PKW(P, B) pkh(P[B], P[B + 1])
; __device__ __forceinline__ void pv(f32x16* o, int vb, f16x8 pa0, f16x8 pa1, f16x8 pa2, f16x8 pa3) {
; #pragma unroll
;     for (int d0 = 0; d0 < 2; ++d0) { f16x4 lo[4], hi[4];
; #pragma unroll
;         for (int ks = 0; ks < 4; ++ks) {
;             asm volatile("ds_read_b64_tr_b16 %0,%1 offset:%c2" : "=&v"(lo[ks]) : "v"(vb), "i"(d0 * 4096 + ks * 1024) : "memory");
;             asm volatile("ds_read_b64_tr_b16 %0,%1 offset:%c2" : "=&v"(hi[ks]) : "v"(vb), "i"(d0 * 4096 + ks * 1024 + 512) : "memory"); }
;         asm volatile("s_waitcnt lgkmcnt(0)" ::: "memory"); SBAR();
;     ...
;         o[d0] = __builtin_amdgcn_mfma_f32_32x32x16_f16(pa0, PK(0), o[d0], 0, 0, 0);
;         o[d0] = __builtin_amdgcn_mfma_f32_32x32x16_f16(pa1, PK(1), o[d0], 0, 0, 0);
;         o[d0] = __builtin_amdgcn_mfma_f32_32x32x16_f16(pa2, PK(2), o[d0], 0, 0, 0);
;         o[d0] = __builtin_amdgcn_mfma_f32_32x32x16_f16(pa3, PK(3), o[d0], 0, 0, 0);
;     ...
;     }
; }
; template <int THRL> __device__ __forceinline__ void attn_unit(int b, int h, int qb, const f16_t* Q, const f16_t* __restrict__ K, const f16_t* __restrict__ V, f16_t* O, const float* __restrict__ kms, char* shm) {
;     ...
;     { float sacc = pB0[0] + pB0[1]; _Pragma("unroll") for (int r = 2; r < 16; ++r) sacc += pB0[r]; _Pragma("unroll") for (int r = 0; r < 16; ++r) sacc += pB1[r]; l_reg += sacc;
;       pw0 = (u32x4){PKW(pB0, 0), PKW(pB0, 2), PKW(pB0, 4), PKW(pB0, 6)}; pw1 = (u32x4){PKW(pB0, 8), PKW(pB0, 10), PKW(pB0, 12), PKW(pB0, 14)}; pw2 = (u32x4){PKW(pB1, 0), PKW(pB1, 2), PKW(pB1, 4), PKW(pB1, 6)}; pw3 = (u32x4){PKW(pB1, 8), PKW(pB1, 10), PKW(pB1, 12), PKW(pB1, 14)};
;       SBAR(); pv(o, vb0 + sl_cur, PAF(0), PAF(1), PAF(2), PAF(3)); }
;     ...
;     { auto rr = __builtin_amdgcn_permlane32_swap(__float_as_uint(l_reg), __float_as_uint(l_reg), false, false); l_reg = __uint_as_float(rr[0]) + __uint_as_float(rr[1]); }
;     if (hi == 0) wsf[32 + r32] = l_reg; asm volatile("s_waitcnt lgkmcnt(0)" ::: "memory");
.LBB0_565:
	v_add_f32_e32 v51, v82, v83
	v_add_f32_e32 v51, v84, v51
	v_add_f32_e32 v51, v85, v51
	v_add_f32_e32 v51, v86, v51
	v_add_f32_e32 v51, v87, v51
	v_add_f32_e32 v51, v88, v51
	v_add_f32_e32 v51, v89, v51
	v_add_f32_e32 v51, v90, v51
	v_add_f32_e32 v51, v91, v51
	v_add_f32_e32 v51, v92, v51
	v_add_f32_e32 v51, v93, v51
	v_add_f32_e32 v51, v94, v51
	v_add_f32_e32 v51, v95, v51
	v_add_f32_e32 v51, v96, v51
	v_add_f32_e32 v51, v97, v51
	v_add_f32_e32 v51, v34, v51
	v_add_f32_e32 v51, v35, v51
	v_add_f32_e32 v51, v36, v51
	v_add_f32_e32 v51, v37, v51
	v_add_f32_e32 v51, v38, v51
	v_add_f32_e32 v51, v39, v51
	v_add_f32_e32 v51, v40, v51
	v_add_f32_e32 v51, v41, v51
	v_add_f32_e32 v51, v42, v51
	v_add_f32_e32 v51, v43, v51
	v_add_f32_e32 v51, v44, v51
	v_add_f32_e32 v51, v45, v51
	v_add_f32_e32 v51, v46, v51
	v_add_f32_e32 v51, v47, v51
	s_cmp_lg_u32 0, -1
	v_add_f32_e32 v51, v48, v51
	s_cselect_b32 s2, 0, 0
	v_add_f32_e32 v51, v49, v51
	s_addk_i32 s2, 0x6000
	v_add_f32_e32 v51, v114, v51
	v_cvt_pk_f16_f32 v34, v34, v35
	v_add3_u32 v60, v206, s2, v203
	v_cvt_pk_f16_f32 v52, v82, v83
	v_cvt_pk_f16_f32 v53, v84, v85
	v_cvt_pk_f16_f32 v54, v86, v87
	v_cvt_pk_f16_f32 v55, v88, v89
	v_cvt_pk_f16_f32 v56, v90, v91
	v_cvt_pk_f16_f32 v57, v92, v93
	v_cvt_pk_f16_f32 v58, v94, v95
	v_cvt_pk_f16_f32 v59, v96, v97
	v_cvt_pk_f16_f32 v35, v36, v37
	v_cvt_pk_f16_f32 v36, v38, v39
	v_cvt_pk_f16_f32 v37, v40, v41
	v_cvt_pk_f16_f32 v38, v42, v43
	v_cvt_pk_f16_f32 v39, v44, v45
	v_cvt_pk_f16_f32 v40, v46, v47
	v_cvt_pk_f16_f32 v41, v48, v49
	v_readlane_b32 s98, v254, 29
	s_nop 1
	v_mov_b32_e32 v250, s98
	v_lshlrev_b32_e32 v250, 16, v250
	v_add_u32_e32 v250, 0x64f8800, v250
	v_lshl_add_u32 v250, v0, 7, v250
	global_load_dword v251, v250, s[22:23]
	v_add_u32_e32 v250, 0x10000, v250
	global_load_dword v252, v250, s[22:23]
	v_add3_u32 v68, v60, v205, s11
	ds_read_b64_tr_b16 v[42:43],v68 offset:0
	ds_read_b64_tr_b16 v[44:45],v68 offset:512
	ds_read_b64_tr_b16 v[46:47],v68 offset:1024
	ds_read_b64_tr_b16 v[48:49],v68 offset:1536
	ds_read_b64_tr_b16 v[60:61],v68 offset:2048
	ds_read_b64_tr_b16 v[62:63],v68 offset:2560
	ds_read_b64_tr_b16 v[64:65],v68 offset:3072
	ds_read_b64_tr_b16 v[66:67],v68 offset:3584
	s_waitcnt lgkmcnt(0)
	s_nop 0
	v_mfma_f32_32x32x16_f16 v[18:33], v[52:55], v[42:45], v[18:33]
	ds_read_b64_tr_b16 v[42:43],v68 offset:4096
	ds_read_b64_tr_b16 v[44:45],v68 offset:4608
	v_mfma_f32_32x32x16_f16 v[18:33], v[56:59], v[46:49], v[18:33]
	ds_read_b64_tr_b16 v[46:47],v68 offset:5120
	ds_read_b64_tr_b16 v[48:49],v68 offset:5632
	v_mfma_f32_32x32x16_f16 v[18:33], v[34:37], v[60:63], v[18:33]
	ds_read_b64_tr_b16 v[60:61],v68 offset:6144
	ds_read_b64_tr_b16 v[62:63],v68 offset:6656
	v_mfma_f32_32x32x16_f16 v[18:33], v[38:41], v[64:67], v[18:33]
	ds_read_b64_tr_b16 v[64:65],v68 offset:7168
	ds_read_b64_tr_b16 v[66:67],v68 offset:7680
	s_waitcnt lgkmcnt(0)
	v_mfma_f32_32x32x16_f16 v[2:17], v[52:55], v[42:45], v[2:17]
	v_cmp_gt_u32_e32 vcc, 32, v201
	v_mfma_f32_32x32x16_f16 v[2:17], v[56:59], v[46:49], v[2:17]
	v_mfma_f32_32x32x16_f16 v[2:17], v[34:37], v[60:63], v[2:17]
	v_mov_b32_e32 v34, v51
	s_nop 1
	v_permlane32_swap_b32_e32 v51, v34
	v_mfma_f32_32x32x16_f16 v[2:17], v[38:41], v[64:67], v[2:17]
	s_and_saveexec_b64 s[2:3], vcc
	s_cbranch_execz .LBB0_529
	v_add_f32_e32 v34, v51, v34
	ds_write_b32 v207, v34 offset:49280
	s_branch .LBB0_529
